# mLSTM: no VMEM issue right after the interval-A barrier (store-drain window); raw q/k row loads regrouped 0/5/2 over the three step-3 points
# speedup vs baseline: 1.0076x; 1.0074x over previous
.LBB0_264:
	s_cmpk_eq_i32 s82, 0x7c0
	s_cbranch_scc1 .Lmls_1
	buffer_load_dwordx4 v[104:107], v104, s[76:79], 0 offen offset:2048 sc1
	buffer_load_dwordx4 v[100:103], v100, s[76:79], 0 offen sc1
	buffer_load_dwordx4 v[108:111], v108, s[76:79], 0 offen offset:2048 sc1
	buffer_load_dwordx4 v[112:115], v112, s[76:79], 0 offen sc1
	buffer_load_dwordx4 v[116:119], v116, s[76:79], 0 offen offset:2048 sc1
